# GEMM loops: per-phase s_setprio flips removed, one static s_setprio 1 for the older wave half (wr==0) per GEMM phase, reset after
# baseline (speedup 1.0000x reference)
.LBB0_236:
	s_or_b64 exec, exec, s[0:1]
	v_lshrrev_b32_e32 v2, 1, v144
	v_and_b32_e32 v11, 24, v2
	v_lshrrev_b32_e32 v2, 5, v144
	v_and_b32_e32 v2, 4, v2
	v_bfe_u32 v3, v144, 2, 2
	v_lshlrev_b32_e32 v0, 4, v144
	v_and_b32_e32 v1, 32, v144
	v_bfe_u32 v10, v144, 2, 4
	v_or3_b32 v2, v2, v3, v11
	v_lshrrev_b32_e32 v3, 3, v144
	s_movk_i32 s0, 0x70
	v_bitop3_b32 v8, v0, v1, 48 bitop3:0x6c
	v_and_b32_e32 v9, 64, v144
	v_and_or_b32 v4, v3, s0, v10
	s_movk_i32 s0, 0x60
	v_add_u32_e32 v12, 0x2000, v0
	v_or_b32_e32 v1, v8, v9
	v_and_or_b32 v3, v3, s0, v2
	v_lshrrev_b32_e32 v0, 7, v12
	s_movk_i32 s0, 0xf0
	v_readfirstlane_b32 s2, v144
	v_lshl_or_b32 v130, v3, 12, v1
	v_and_or_b32 v3, v0, s0, v10
	s_movk_i32 s0, 0xe0
	v_and_or_b32 v0, v0, s0, v2
	s_lshr_b32 s6, s2, 6
	s_or_b32 s66, s12, 64
	s_lshr_b32 s0, s3, 3
	s_mov_b32 s1, 0
	s_lshr_b32 s8, s2, 8
	s_lshl_b32 s33, s6, 10
	s_lshl_b32 s7, s66, 20
	s_lshl_b64 s[10:11], s[0:1], 20
	s_add_u32 s36, s22, s10
	s_addc_u32 s37, s23, s11
	s_add_i32 s56, s33, 0
	s_add_i32 m0, s56, 0x10000
	s_barrier
	global_load_lds_dwordx4 v130, s[36:37]
	s_add_i32 m0, s56, 0x12000
	v_lshl_or_b32 v134, v0, 12, v1
	s_add_u32 s18, s34, s7
	v_lshl_or_b32 v128, v4, 12, v1
	global_load_lds_dwordx4 v134, s[36:37]
	s_addc_u32 s19, s35, 0
	s_mov_b32 m0, s56
	s_add_i32 s57, s56, 0x2000
	v_lshl_or_b32 v132, v3, 12, v1
	global_load_lds_dwordx4 v128, s[18:19]
	s_mov_b32 m0, s57
	s_add_u32 s10, s36, 0x80000
	global_load_lds_dwordx4 v132, s[18:19]
	s_addc_u32 s11, s37, 0
	s_add_i32 m0, s56, 0x14000
	v_mov_b32_e32 v131, 0
	global_load_lds_dwordx4 v130, s[10:11]
	s_add_i32 m0, s56, 0x16000
	v_mov_b32_e32 v135, v131
	global_load_lds_dwordx4 v134, s[10:11]
	s_add_u32 s10, s18, 0x80000
	s_addc_u32 s11, s19, 0
	s_add_i32 s58, s56, 0x4000
	s_mov_b32 m0, s58
	s_add_i32 s59, s56, 0x6000
	global_load_lds_dwordx4 v128, s[10:11]
	s_mov_b32 m0, s59
	v_mov_b32_e32 v129, v131
	global_load_lds_dwordx4 v132, s[10:11]
	v_mov_b32_e32 v133, v131
	v_lshl_add_u64 v[6:7], s[36:37], 0, v[130:131]
	v_lshl_add_u64 v[4:5], s[36:37], 0, v[134:135]
	v_lshl_add_u64 v[2:3], s[18:19], 0, v[128:129]
	s_setprio 1
	s_cmp_lg_u32 s8, 1
	v_lshl_add_u64 v[0:1], s[18:19], 0, v[132:133]
	s_cbranch_scc1 .LBB0_238
	s_setprio 0
	s_barrier

.LBB0_315:
	s_andn2_b64 vcc, exec, s[8:9]
	s_cbranch_vccnz .LBB0_398
	s_waitcnt vmcnt(0)
	v_lshrrev_b32_e32 v2, 1, v144
	v_and_b32_e32 v11, 24, v2
	v_lshrrev_b32_e32 v2, 5, v144
	v_and_b32_e32 v2, 4, v2
	v_bfe_u32 v3, v144, 2, 2
	v_lshlrev_b32_e32 v0, 4, v144
	v_and_b32_e32 v1, 32, v144
	v_bfe_u32 v10, v144, 2, 4
	v_or3_b32 v2, v2, v3, v11
	v_lshrrev_b32_e32 v3, 3, v144
	s_movk_i32 s1, 0x70
	v_bitop3_b32 v8, v0, v1, 48 bitop3:0x6c
	v_and_b32_e32 v9, 64, v144
	v_and_or_b32 v4, v3, s1, v10
	s_movk_i32 s1, 0x60
	v_add_u32_e32 v12, 0x2000, v0
	v_or_b32_e32 v1, v8, v9
	v_and_or_b32 v3, v3, s1, v2
	v_lshrrev_b32_e32 v0, 7, v12
	s_movk_i32 s1, 0xf0
	s_add_u32 s58, s22, 0x5e00000
	v_lshl_or_b32 v130, v3, 12, v1
	v_and_or_b32 v3, v0, s1, v10
	s_movk_i32 s1, 0xe0
	s_addc_u32 s59, s23, 0
	v_and_or_b32 v0, v0, s1, v2
	s_lshr_b32 s10, s33, 6
	s_ashr_i32 s1, s0, 31
	s_ashr_i32 s35, s34, 31
	s_lshr_b32 s12, s33, 8
	s_lshl_b32 s60, s10, 10
	s_lshl_b64 s[8:9], s[0:1], 20
	s_lshl_b64 s[14:15], s[34:35], 20
	s_add_u32 s54, s22, s14
	s_addc_u32 s55, s23, s15
	s_add_i32 s61, s60, 0
	s_add_i32 m0, s61, 0x10000
	v_lshl_or_b32 v134, v0, 12, v1
	global_load_lds_dwordx4 v130, s[54:55]
	s_add_i32 m0, s61, 0x12000
	s_waitcnt lgkmcnt(0)
	s_add_u32 s36, s58, s8
	v_lshl_or_b32 v128, v4, 12, v1
	global_load_lds_dwordx4 v134, s[54:55]
	s_addc_u32 s37, s59, s9
	s_mov_b32 m0, s61
	s_add_i32 s62, s61, 0x2000
	v_lshl_or_b32 v132, v3, 12, v1
	global_load_lds_dwordx4 v128, s[36:37]
	s_mov_b32 m0, s62
	s_add_u32 s8, s54, 0x80000
	global_load_lds_dwordx4 v132, s[36:37]
	s_addc_u32 s9, s55, 0
	s_add_i32 m0, s61, 0x14000
	v_mov_b32_e32 v131, 0
	global_load_lds_dwordx4 v130, s[8:9]
	s_add_i32 m0, s61, 0x16000
	v_mov_b32_e32 v135, v131
	global_load_lds_dwordx4 v134, s[8:9]
	s_add_u32 s8, s36, 0x80000
	s_addc_u32 s9, s37, 0
	s_add_i32 s63, s61, 0x4000
	s_mov_b32 m0, s63
	s_add_i32 s64, s61, 0x6000
	global_load_lds_dwordx4 v128, s[8:9]
	s_mov_b32 m0, s64
	v_mov_b32_e32 v129, v131
	global_load_lds_dwordx4 v132, s[8:9]
	v_mov_b32_e32 v133, v131
	s_mov_b32 s65, 0
	v_lshl_add_u64 v[6:7], s[54:55], 0, v[130:131]
	v_lshl_add_u64 v[4:5], s[54:55], 0, v[134:135]
	v_lshl_add_u64 v[2:3], s[36:37], 0, v[128:129]
	s_setprio 1
	s_cmp_lg_u32 s12, 1
	v_lshl_add_u64 v[0:1], s[36:37], 0, v[132:133]
	s_cbranch_scc1 .LBB0_318
	s_setprio 0
	s_barrier

.LBB0_920:
	s_waitcnt vmcnt(0)
	v_lshlrev_b32_e32 v2, 1, v145
	v_lshrrev_b32_e32 v3, 5, v144
	s_ashr_i32 s6, s8, 3
	v_and_b32_e32 v2, 24, v2
	v_and_b32_e32 v3, 4, v3
	v_and_b32_e32 v4, 3, v145
	s_waitcnt lgkmcnt(0)
	s_add_u32 s42, s22, 0x14a00000
	v_lshlrev_b32_e32 v0, 4, v144
	v_and_b32_e32 v1, 32, v144
	v_and_b32_e32 v10, 15, v145
	v_or3_b32 v2, v3, v4, v2
	v_lshrrev_b32_e32 v3, 3, v144
	s_movk_i32 s7, 0x70
	s_addc_u32 s43, s23, 0
	v_bitop3_b32 v8, v0, v1, 48 bitop3:0x6c
	v_and_b32_e32 v9, 64, v144
	v_and_or_b32 v4, v3, s7, v10
	s_movk_i32 s7, 0x60
	v_add_u32_e32 v11, 0x2000, v0
	s_add_u32 s44, s22, 0x1000000
	v_or_b32_e32 v1, v8, v9
	v_and_or_b32 v3, v3, s7, v2
	v_lshrrev_b32_e32 v0, 7, v11
	s_movk_i32 s7, 0xf0
	s_addc_u32 s45, s23, 0
	v_lshl_or_b32 v148, v3, 11, v1
	v_and_or_b32 v3, v0, s7, v10
	s_movk_i32 s7, 0xe0
	s_add_i32 s6, s9, s6
	v_and_or_b32 v0, v0, s7, v2
	s_ashr_i32 s7, s6, 31
	s_lshr_b32 s7, s7, 26
	s_add_i32 s7, s6, s7
	s_ashr_i32 s9, s7, 6
	s_andn2_b32 s7, s7, 63
	s_sub_i32 s6, s6, s7
	s_bfe_i32 s7, s6, 0x80000
	s_bfe_u32 s7, s7, 0x3000c
	s_add_i32 s7, s6, s7
	s_bfe_i32 s10, s7, 0x80000
	s_and_b32 s7, s7, 0xf8
	s_sub_i32 s6, s6, s7
	s_lshl_b32 s9, s9, 3
	s_sext_i32_i16 s10, s10
	s_sext_i32_i8 s6, s6
	s_lshr_b32 s11, s2, 8
	s_lshr_b32 s10, s10, 3
	s_add_i32 s34, s9, s6
	s_lshr_b32 s8, s2, 6
	s_ashr_i32 s35, s34, 31
	s_bfe_i64 s[12:13], s[10:11], 0x100000
	s_lshl_b32 s46, s8, 10
	s_lshl_b64 s[6:7], s[34:35], 19
	s_lshl_b64 s[12:13], s[12:13], 19
	s_add_u32 s38, s44, s12
	s_addc_u32 s39, s45, s13
	s_add_i32 s35, s46, 0
	s_add_i32 m0, s35, 0x10000
	v_lshl_or_b32 v152, v0, 11, v1
	global_load_lds_dwordx4 v148, s[38:39]
	s_add_i32 m0, s35, 0x12000
	s_add_u32 s36, s42, s6
	v_lshl_or_b32 v146, v4, 11, v1
	global_load_lds_dwordx4 v152, s[38:39]
	s_addc_u32 s37, s43, s7
	s_mov_b32 m0, s35
	s_add_i32 s47, s35, 0x2000
	v_lshl_or_b32 v150, v3, 11, v1
	global_load_lds_dwordx4 v146, s[36:37]
	s_mov_b32 m0, s47
	s_add_u32 s6, s38, 0x40000
	global_load_lds_dwordx4 v150, s[36:37]
	s_addc_u32 s7, s39, 0
	s_add_i32 m0, s35, 0x14000
	v_mov_b32_e32 v149, 0
	global_load_lds_dwordx4 v148, s[6:7]
	s_add_i32 m0, s35, 0x16000
	v_mov_b32_e32 v153, v149
	global_load_lds_dwordx4 v152, s[6:7]
	s_add_u32 s6, s36, 0x40000
	s_addc_u32 s7, s37, 0
	s_add_i32 s48, s35, 0x4000
	s_mov_b32 m0, s48
	s_add_i32 s49, s35, 0x6000
	global_load_lds_dwordx4 v146, s[6:7]
	s_mov_b32 m0, s49
	v_mov_b32_e32 v147, v149
	global_load_lds_dwordx4 v150, s[6:7]
	v_mov_b32_e32 v151, v149
	s_mov_b32 s50, 0
	v_lshl_add_u64 v[6:7], s[38:39], 0, v[148:149]
	v_lshl_add_u64 v[4:5], s[38:39], 0, v[152:153]
	v_lshl_add_u64 v[2:3], s[36:37], 0, v[146:147]
	s_setprio 1
	s_cmp_lg_u32 s11, 1
	v_lshl_add_u64 v[0:1], s[36:37], 0, v[150:151]
	s_cbranch_scc1 .LBB0_922
	s_setprio 0
	s_barrier

.LBB0_1062:
	s_ashr_i32 s6, s8, 3
	s_waitcnt lgkmcnt(0)
	s_add_u32 s48, s22, 0x5e00000
	s_addc_u32 s49, s23, 0
	s_waitcnt vmcnt(0)
	v_lshlrev_b32_e32 v0, 4, v144
	s_add_u32 s50, s22, 0x1400000
	v_and_b32_e32 v1, 32, v144
	v_bfe_u32 v10, v144, 2, 4
	v_lshrrev_b32_e32 v2, 3, v144
	s_movk_i32 s7, 0x70
	v_add_u32_e32 v11, 0x2000, v0
	s_addc_u32 s51, s23, 0
	v_bitop3_b32 v8, v0, v1, 48 bitop3:0x6c
	v_and_or_b32 v2, v2, s7, v10
	v_lshrrev_b32_e32 v0, 7, v11
	s_movk_i32 s7, 0xf0
	s_add_i32 s6, s9, s6
	v_and_or_b32 v0, v0, s7, v10
	s_ashr_i32 s7, s6, 31
	s_lshr_b32 s7, s7, 26
	s_add_i32 s7, s6, s7
	s_ashr_i32 s9, s7, 6
	s_andn2_b32 s7, s7, 63
	s_sub_i32 s6, s6, s7
	s_bfe_i32 s7, s6, 0x80000
	s_bfe_u32 s7, s7, 0x3000c
	s_add_i32 s7, s6, s7
	s_bfe_i32 s10, s7, 0x80000
	s_and_b32 s7, s7, 0xf8
	s_sub_i32 s6, s6, s7
	s_lshl_b32 s9, s9, 3
	s_sext_i32_i16 s10, s10
	s_sext_i32_i8 s6, s6
	s_lshr_b32 s11, s2, 8
	s_lshr_b32 s10, s10, 3
	s_add_i32 s40, s9, s6
	s_lshr_b32 s8, s2, 6
	s_ashr_i32 s41, s40, 31
	s_bfe_i64 s[12:13], s[10:11], 0x100000
	s_lshl_b32 s54, s8, 10
	s_lshl_b64 s[6:7], s[40:41], 20
	s_lshl_b64 s[12:13], s[12:13], 20
	v_and_b32_e32 v9, 64, v144
	s_add_u32 s44, s50, s12
	v_or_b32_e32 v1, v8, v9
	s_addc_u32 s45, s51, s13
	s_add_i32 s41, s54, 0
	v_lshl_or_b32 v146, v2, 12, v1
	s_add_i32 m0, s41, 0x10000
	v_lshl_or_b32 v148, v0, 12, v1
	global_load_lds_dwordx4 v146, s[44:45]
	s_add_i32 m0, s41, 0x12000
	s_add_u32 s42, s48, s6
	global_load_lds_dwordx4 v148, s[44:45]
	s_addc_u32 s43, s49, s7
	s_mov_b32 m0, s41
	s_add_i32 s55, s41, 0x2000
	global_load_lds_dwordx4 v146, s[42:43]
	s_mov_b32 m0, s55
	s_add_u32 s6, s44, 0x80000
	global_load_lds_dwordx4 v148, s[42:43]
	s_addc_u32 s7, s45, 0
	s_add_i32 m0, s41, 0x14000
	v_mov_b32_e32 v147, 0
	global_load_lds_dwordx4 v146, s[6:7]
	s_add_i32 m0, s41, 0x16000
	v_mov_b32_e32 v149, v147
	global_load_lds_dwordx4 v148, s[6:7]
	s_add_u32 s6, s42, 0x80000
	s_addc_u32 s7, s43, 0
	s_add_i32 s56, s41, 0x4000
	s_mov_b32 m0, s56
	s_add_i32 s57, s41, 0x6000
	global_load_lds_dwordx4 v146, s[6:7]
	s_mov_b32 m0, s57
	s_mov_b32 s58, 0
	global_load_lds_dwordx4 v148, s[6:7]
	v_lshl_add_u64 v[6:7], s[44:45], 0, v[146:147]
	v_lshl_add_u64 v[4:5], s[44:45], 0, v[148:149]
	v_lshl_add_u64 v[2:3], s[42:43], 0, v[146:147]
	s_setprio 1
	s_cmp_lg_u32 s11, 1
	v_lshl_add_u64 v[0:1], s[42:43], 0, v[148:149]
	s_cbranch_scc1 .LBB0_1064
	s_setprio 0
	s_barrier

.LBB0_1193:
	s_cmp_lt_i32 s24, 9
	s_cselect_b64 s[0:1], -1, 0
	s_and_b64 s[0:1], s[0:1], s[6:7]
	s_andn2_b64 vcc, exec, s[0:1]
	s_cbranch_vccnz .LBB0_1209
	s_cmpk_gt_i32 s3, 0xaff
	v_readfirstlane_b32 s2, v144
	s_cbranch_scc1 .LBB0_1209
	s_waitcnt vmcnt(0)
	v_lshrrev_b32_e32 v0, 5, v144
	v_lshrrev_b32_e32 v2, 1, v144
	v_and_b32_e32 v0, 4, v0
	v_bfe_u32 v1, v144, 2, 2
	v_and_b32_e32 v11, 24, v2
	v_or3_b32 v0, v0, v1, v11
	v_lshlrev_b32_e32 v1, 4, v144
	v_add_u32_e32 v8, 0x2000, v1
	v_lshrrev_b32_e32 v2, 7, v8
	s_movk_i32 s6, 0xe0
	v_and_b32_e32 v4, 32, v144
	s_add_u32 s33, s22, 0x5e00000
	v_and_or_b32 v3, v2, s6, v0
	v_bitop3_b32 v9, v1, v4, 48 bitop3:0x6c
	v_and_b32_e32 v10, 64, v144
	v_bfe_u32 v12, v144, 2, 4
	s_movk_i32 s6, 0xf0
	s_waitcnt lgkmcnt(0)
	s_addc_u32 s40, s23, 0
	v_or_b32_e32 v1, v9, v10
	v_and_or_b32 v2, v2, s6, v12
	s_add_u32 s41, s22, 0x1c00000
	v_lshl_or_b32 v130, v2, 12, v1
	v_lshrrev_b32_e32 v2, 3, v144
	s_movk_i32 s6, 0x60
	s_addc_u32 s42, s23, 0
	v_and_or_b32 v0, v2, s6, v0
	s_movk_i32 s6, 0x70
	s_ashr_i32 s44, s3, 31
	v_lshl_or_b32 v132, v0, 12, v1
	v_and_or_b32 v0, v2, s6, v12
	s_lshr_b32 s6, s44, 29
	s_add_i32 s6, s3, s6
	s_lshr_b32 s8, s2, 6
	s_ashr_i32 s7, s6, 3
	s_and_b32 s6, s6, -8
	s_lshr_b32 s11, s2, 8
	s_lshl_b32 s43, s8, 10
	s_sub_i32 s6, s3, s6
	s_cmp_lt_i32 s6, 0
	s_movk_i32 s45, 0x161
	s_cselect_b32 s9, s45, 0x160
	s_mul_i32 s6, s6, s9
	s_add_i32 s6, s6, s7
	s_mul_hi_i32 s7, s6, 0x2e8ba2e9
	s_lshr_b32 s9, s7, 31
	s_ashr_i32 s7, s7, 6
	s_add_i32 s7, s7, s9
	s_lshl_b32 s9, s7, 3
	s_mulk_i32 s7, 0x160
	s_sub_i32 s6, s6, s7
	s_sext_i32_i16 s7, s6
	s_bfe_u32 s7, s7, 0x3001c
	s_add_i32 s7, s6, s7
	s_sext_i32_i16 s10, s7
	s_and_b32 s7, s7, 0xfff8
	s_sub_i32 s6, s6, s7
	s_sext_i32_i16 s6, s6
	s_lshr_b32 s10, s10, 3
	s_add_i32 s30, s9, s6
	s_ashr_i32 s31, s30, 31
	s_bfe_i64 s[12:13], s[10:11], 0x100000
	s_lshl_b64 s[6:7], s[30:31], 20
	s_lshl_b64 s[12:13], s[12:13], 20
	s_add_u32 s36, s41, s12
	s_addc_u32 s37, s42, s13
	s_add_i32 s31, s43, 0
	s_add_i32 m0, s31, 0x10000
	v_lshl_or_b32 v128, v3, 12, v1
	global_load_lds_dwordx4 v132, s[36:37]
	s_add_i32 m0, s31, 0x12000
	s_add_u32 s34, s33, s6
	v_lshl_or_b32 v134, v0, 12, v1
	global_load_lds_dwordx4 v128, s[36:37]
	s_addc_u32 s35, s40, s7
	s_mov_b32 m0, s31
	s_add_i32 s46, s31, 0x2000
	global_load_lds_dwordx4 v134, s[34:35]
	s_mov_b32 m0, s46
	s_add_u32 s6, s36, 0x80000
	global_load_lds_dwordx4 v130, s[34:35]
	s_addc_u32 s7, s37, 0
	s_add_i32 m0, s31, 0x14000
	v_mov_b32_e32 v133, 0
	global_load_lds_dwordx4 v132, s[6:7]
	s_add_i32 m0, s31, 0x16000
	v_mov_b32_e32 v129, v133
	global_load_lds_dwordx4 v128, s[6:7]
	s_add_u32 s6, s34, 0x80000
	s_addc_u32 s7, s35, 0
	s_add_i32 s47, s31, 0x4000
	s_mov_b32 m0, s47
	s_add_i32 s48, s31, 0x6000
	global_load_lds_dwordx4 v134, s[6:7]
	s_mov_b32 m0, s48
	v_mov_b32_e32 v135, v133
	global_load_lds_dwordx4 v130, s[6:7]
	v_mov_b32_e32 v131, v133
	s_mov_b32 s49, 0
	v_lshl_add_u64 v[6:7], s[36:37], 0, v[132:133]
	v_lshl_add_u64 v[4:5], s[36:37], 0, v[128:129]
	v_lshl_add_u64 v[2:3], s[34:35], 0, v[134:135]
	s_setprio 1
	s_cmp_lg_u32 s11, 1
	v_lshl_add_u64 v[0:1], s[34:35], 0, v[130:131]
	s_cbranch_scc1 .LBB0_1197
	s_setprio 0
	s_barrier

.LBB0_1269:
	s_waitcnt lgkmcnt(0)
	s_add_u32 s42, s22, 0xa600000
	s_addc_u32 s43, s23, 0
	s_add_u32 s44, s22, 0x4800000
	s_addc_u32 s45, s23, 0
	s_add_i32 s1, s8, s1
	s_waitcnt vmcnt(0)
	v_lshlrev_b32_e32 v0, 4, v144
	v_and_b32_e32 v1, 32, v144
	s_ashr_i32 s8, s1, 31
	v_bfe_u32 v2, v144, 2, 4
	v_bitop3_b32 v8, v0, v1, 48 bitop3:0x6c
	v_lshrrev_b32_e32 v3, 3, v144
	s_movk_i32 s9, 0x70
	v_add_u32_e32 v0, 0x2000, v0
	s_lshr_b32 s8, s8, 26
	v_and_or_b32 v3, v3, s9, v2
	v_lshrrev_b32_e32 v0, 7, v0
	s_movk_i32 s9, 0xf0
	s_add_i32 s8, s1, s8
	v_and_or_b32 v0, v0, s9, v2
	s_ashr_i32 s9, s8, 6
	s_and_b32 s8, s8, 0xffc0
	s_sub_i32 s8, s1, s8
	s_bfe_i32 s1, s8, 0x80000
	s_bfe_u32 s1, s1, 0x3000c
	s_add_i32 s11, s8, s1
	s_bfe_i32 s1, s11, 0x80000
	s_and_b32 s11, s11, 0xf8
	s_sext_i32_i16 s12, s1
	s_sub_i32 s8, s8, s11
	s_lshr_b32 s10, s2, 6
	s_lshl_b32 s9, s9, 3
	s_sext_i32_i8 s8, s8
	s_ashr_i32 s11, s12, 3
	s_lshr_b32 s0, s2, 8
	s_lshl_b32 s46, s10, 10
	s_lshr_b32 s1, s12, 3
	s_add_i32 s66, s9, s8
	s_mul_hi_i32 s12, s11, 0x2c0000
	s_mul_i32 s11, s11, 0x2c0000
	v_and_b32_e32 v9, 64, v144
	s_add_u32 s38, s44, s11
	v_or_b32_e32 v1, v8, v9
	v_mul_u32_u24_e32 v10, 0x2c00, v3
	s_addc_u32 s39, s45, s12
	s_add_i32 s47, s46, 0
	v_or_b32_e32 v146, v10, v1
	s_add_i32 m0, s47, 0x10000
	v_mul_u32_u24_e32 v11, 0x2c00, v0
	s_mul_i32 s9, s66, 0x2c0000
	global_load_lds_dwordx4 v146, s[38:39]
	s_add_i32 m0, s47, 0x12000
	v_or_b32_e32 v148, v11, v1
	s_mul_hi_i32 s8, s66, 0x2c0000
	s_add_u32 s36, s42, s9
	global_load_lds_dwordx4 v148, s[38:39]
	s_addc_u32 s37, s43, s8
	s_mov_b32 m0, s47
	s_add_i32 s48, s47, 0x2000
	global_load_lds_dwordx4 v146, s[36:37]
	s_mov_b32 m0, s48
	s_add_u32 s8, s38, 0x160000
	global_load_lds_dwordx4 v148, s[36:37]
	s_addc_u32 s9, s39, 0
	s_add_i32 m0, s47, 0x14000
	v_mov_b32_e32 v147, 0
	global_load_lds_dwordx4 v146, s[8:9]
	s_add_i32 m0, s47, 0x16000
	v_mov_b32_e32 v149, v147
	global_load_lds_dwordx4 v148, s[8:9]
	s_add_u32 s8, s36, 0x160000
	s_addc_u32 s9, s37, 0
	s_add_i32 s49, s47, 0x4000
	s_mov_b32 m0, s49
	s_add_i32 s50, s47, 0x6000
	global_load_lds_dwordx4 v146, s[8:9]
	s_mov_b32 m0, s50
	s_mov_b32 s51, 0
	global_load_lds_dwordx4 v148, s[8:9]
	v_lshl_add_u64 v[6:7], s[38:39], 0, v[146:147]
	v_lshl_add_u64 v[4:5], s[38:39], 0, v[148:149]
	v_lshl_add_u64 v[2:3], s[36:37], 0, v[146:147]
	s_setprio 1
	s_cmp_lg_u32 s0, 1
	v_lshl_add_u64 v[0:1], s[36:37], 0, v[148:149]
	s_cbranch_scc1 .LBB0_1271
	s_setprio 0
	s_barrier
